# proj GEMM walks its column tiles in reverse (gates first, hyena/QKV columns last) so the next phase finds its inputs still cached
# speedup vs baseline: 1.0127x; 1.0127x over previous
.LBB0_398:
	s_mov_b64 s[2:3], s[96:97]
	s_mov_b32 s4, s94
	s_mov_b32 s5, s93
	s_cmpk_lt_i32 s5, 0x880
	v_mov_b32_e32 v8, v192
	s_cselect_b64 s[18:19], -1, 0
	s_and_b64 vcc, exec, s[18:19]
	v_readfirstlane_b32 s6, v8
	s_cbranch_vccz .LBB0_400
	s_ashr_i32 s7, s5, 31
	s_lshr_b32 s7, s7, 29
	s_add_i32 s7, s5, s7
	s_ashr_i32 s8, s7, 3
	s_and_b32 s7, s7, -8
	s_sub_i32 s7, s5, s7
	s_cmp_lt_i32 s7, 0
	s_movk_i32 s9, 0x111
	s_cselect_b32 s9, s9, 0x110
	s_mul_i32 s7, s9, s7
	s_add_i32 s7, s7, s8
	s_mul_hi_i32 s8, s7, 0x78787879
	s_lshr_b32 s9, s8, 31
	s_ashr_i32 s8, s8, 7
	s_add_i32 s8, s8, s9
	s_lshl_b32 s9, s8, 3
	s_mulk_i32 s8, 0x110
	s_sub_i32 s7, s7, s8
	s_bfe_u32 s8, s7, 0x3001c
	s_add_i32 s8, s7, s8
	s_sext_i32_i16 s10, s8
	s_and_b32 s8, s8, 0xfff8
	s_sub_i32 s7, s7, s8
	s_sext_i32_i16 s7, s7
	s_add_i32 s44, s9, s7
	s_ashr_i32 s42, s10, 3
	s_sub_i32 s42, 33, s42

.LBB0_405:
	s_add_i32 s86, s86, 1
	s_mul_i32 s18, s86, s76
	s_mul_hi_u32 s19, s86, s4
	s_add_i32 s19, s19, s18
	s_mul_i32 s18, s86, s4
	s_add_u32 s34, s18, s5
	s_addc_u32 s35, s19, s77
	v_mov_b64_e32 v[0:1], 0x87f
	v_cmp_gt_i64_e64 s[40:41], s[34:35], v[0:1]
	s_and_b64 vcc, exec, s[40:41]
	s_cbranch_vccnz .LBB0_407
	s_ashr_i32 s18, s34, 31
	s_lshr_b32 s18, s18, 29
	s_add_i32 s18, s34, s18
	s_ashr_i32 s19, s18, 3
	s_and_b32 s18, s18, -8
	s_sub_i32 s18, s34, s18
	s_cmp_lt_i32 s18, 0
	s_movk_i32 s43, 0x111
	s_cselect_b32 s43, s43, 0x110
	s_mul_i32 s18, s43, s18
	s_add_i32 s18, s18, s19
	s_mul_hi_i32 s19, s18, 0x78787879
	s_lshr_b32 s43, s19, 31
	s_ashr_i32 s19, s19, 7
	s_add_i32 s19, s19, s43
	s_lshl_b32 s43, s19, 3
	s_sub_i32 s45, 64, s43
	s_min_i32 s45, s45, 8
	s_abs_i32 s62, s45
	v_cvt_f32_u32_e32 v0, s62
	s_sub_i32 s64, 0, s62
	s_mulk_i32 s19, 0x110
	s_sub_i32 s18, s18, s19
	v_rcp_iflag_f32_e32 v0, v0
	s_abs_i32 s19, s18
	s_xor_b32 s63, s18, s45
	s_ashr_i32 s63, s63, 31
	v_mul_f32_e32 v0, 0x4f7ffffe, v0
	v_cvt_u32_f32_e32 v0, v0
	s_nop 0
	v_readfirstlane_b32 s65, v0
	s_mul_i32 s64, s64, s65
	s_mul_hi_u32 s64, s65, s64
	s_add_i32 s65, s65, s64
	s_mul_hi_u32 s64, s19, s65
	s_mul_i32 s65, s64, s62
	s_sub_i32 s19, s19, s65
	s_add_i32 s66, s64, 1
	s_sub_i32 s65, s19, s62
	s_cmp_ge_u32 s19, s62
	s_cselect_b32 s64, s66, s64
	s_cselect_b32 s19, s65, s19
	s_add_i32 s65, s64, 1
	s_cmp_ge_u32 s19, s62
	s_cselect_b32 s19, s65, s64
	s_xor_b32 s19, s19, s63
	s_sub_i32 s62, s19, s63
	s_mul_i32 s19, s62, s45
	s_sub_i32 s18, s18, s19
	s_add_i32 s64, s18, s43
	s_sub_i32 s62, 33, s62
